# on top of v29: 15 adjacent scalar v_add_f32 pairs of the forgetting-attention pipelined step row sums packed into v_pk_add_f32 and two add-zero ops deleted (17 VALU fewer per step)
# baseline (speedup 1.0000x reference)
.LBB0_887:
	s_andn2_b64 vcc, exec, s[4:5]
	s_cbranch_vccnz .LBB0_889
	v_add_u32_e32 v246, s33, v202
	v_add_u32_e32 v246, 0x18a00, v246
	s_nop 6
	v_add_u32_e32 v0, s58, v197
	v_add_u32_e32 v247, s58, v195
	ds_read_b128 v[66:69], v247
	ds_read_b128 v[70:73], v247 offset:4096
	v_add_u32_e32 v248, s58, v198
	ds_read_b128 v[74:77], v248
	ds_read_b128 v[78:81], v248 offset:4096
	v_add_u32_e32 v249, s58, v199
	ds_read_b128 v[82:85], v249
	ds_read_b128 v[86:89], v249 offset:4096
	v_add_u32_e32 v250, s58, v200
	ds_read_b128 v[90:93], v250
	ds_read_b128 v[94:97], v250 offset:4096
	ds_read_b128 v[34:37], v246 offset:256
	ds_read_b128 v[50:53], v246 offset:384
	ds_read_b128 v[38:41], v246 offset:288
	ds_read_b128 v[54:57], v246 offset:416
	ds_read_b128 v[42:45], v246 offset:320
	ds_read_b128 v[58:61], v246 offset:448
	ds_read_b128 v[46:49], v246 offset:352
	ds_read_b128 v[62:65], v246 offset:480
	s_waitcnt lgkmcnt(1)
	v_mfma_f32_32x32x16_bf16 v[34:49], v[66:69], v[146:149], v[34:49]
	s_waitcnt lgkmcnt(0)
	v_mfma_f32_32x32x16_bf16 v[50:65], v[70:73], v[146:149], v[50:65]
	v_mfma_f32_32x32x16_bf16 v[34:49], v[74:77], v[150:153], v[34:49]
	v_mfma_f32_32x32x16_bf16 v[50:65], v[78:81], v[150:153], v[50:65]
	v_mfma_f32_32x32x16_bf16 v[34:49], v[82:85], v[154:157], v[34:49]
	v_mfma_f32_32x32x16_bf16 v[50:65], v[86:89], v[154:157], v[50:65]
	v_mfma_f32_32x32x16_bf16 v[34:49], v[90:93], v[158:161], v[34:49]
	v_mfma_f32_32x32x16_bf16 v[50:65], v[94:97], v[158:161], v[50:65]
	s_add_i32 s4, s58, 0x2000
	ds_read_b128 v[82:85], v247 offset:8192
	ds_read_b128 v[66:69], v246
	ds_read_b128 v[70:73], v246 offset:32
	ds_read_b128 v[74:77], v246 offset:64
	ds_read_b128 v[78:81], v246 offset:96
	s_nop 5
	v_exp_f32_e32 v162, v50
	v_exp_f32_e32 v138, v51
	v_exp_f32_e32 v130, v52
	s_waitcnt lgkmcnt(0)
	v_mfma_f32_32x32x16_bf16 v[66:81], v[82:85], v[146:149], v[66:81]
	ds_read_b128 v[82:85], v248 offset:8192
	ds_read_b128 v[86:89], v250 offset:8192
	v_exp_f32_e32 v122, v34
	v_exp_f32_e32 v134, v35
	v_exp_f32_e32 v126, v36
	v_exp_f32_e32 v116, v37
	s_waitcnt lgkmcnt(1)
	v_mfma_f32_32x32x16_bf16 v[66:81], v[82:85], v[150:153], v[66:81]
	ds_read_b128 v[82:85], v249 offset:8192
	ds_read_b128 v[34:37], v247 offset:12288
	ds_read_b128 v[90:93], v246 offset:192
	ds_read_b128 v[94:97], v246 offset:224
	v_exp_f32_e32 v172, v53
	v_exp_f32_e32 v186, v38
	v_exp_f32_e32 v168, v39
	s_waitcnt lgkmcnt(3)
	v_mfma_f32_32x32x16_bf16 v[66:81], v[82:85], v[154:157], v[66:81]
	ds_read_b128 v[82:85], v246 offset:128
	v_exp_f32_e32 v164, v40
	v_exp_f32_e32 v142, v41
	ds_read_b128 v[38:41], v250 offset:12288
	v_exp_f32_e32 v244, v54
	v_exp_f32_e32 v170, v55
	v_exp_f32_e32 v166, v56
	v_mfma_f32_32x32x16_bf16 v[66:81], v[86:89], v[158:161], v[66:81]
	ds_read_b128 v[86:89], v246 offset:160
	ds_read_b128 v[50:53], v248 offset:12288
	v_exp_f32_e32 v144, v57
	v_exp_f32_e32 v136, v42
	v_exp_f32_e32 v140, v58
	v_exp_f32_e32 v128, v43
	v_exp_f32_e32 v132, v59
	s_waitcnt lgkmcnt(1)
	v_mfma_f32_32x32x16_bf16 v[82:97], v[34:37], v[146:149], v[82:97]
	ds_read_b128 v[34:37], v249 offset:12288
	v_exp_f32_e32 v120, v44
	v_exp_f32_e32 v124, v60
	v_exp_f32_e32 v114, v45
	v_exp_f32_e32 v118, v61
	v_exp_f32_e32 v110, v46
	v_exp_f32_e32 v112, v62
	s_waitcnt lgkmcnt(1)
	v_mfma_f32_32x32x16_bf16 v[82:97], v[50:53], v[150:153], v[82:97]
	v_exp_f32_e32 v104, v47
	v_exp_f32_e32 v108, v63
	v_exp_f32_e32 v102, v48
	v_exp_f32_e32 v98, v49
	v_exp_f32_e32 v106, v64
	v_exp_f32_e32 v100, v65
	s_waitcnt lgkmcnt(0)
	v_mfma_f32_32x32x16_bf16 v[82:97], v[34:37], v[154:157], v[82:97]
	v_mfma_f32_32x32x16_bf16 v[82:97], v[38:41], v[158:161], v[82:97]
	v_cvt_pk_bf16_f32 v213, v126, v116
	v_cvt_pk_bf16_f32 v214, v186, v168
	v_cvt_pk_bf16_f32 v215, v164, v142
	v_cvt_pk_bf16_f32 v174, v136, v128
	v_cvt_pk_bf16_f32 v175, v120, v114
	v_cvt_pk_bf16_f32 v176, v110, v104
	v_cvt_pk_bf16_f32 v177, v102, v98
	v_cvt_pk_bf16_f32 v178, v162, v138
	v_cvt_pk_bf16_f32 v179, v130, v172
	v_cvt_pk_bf16_f32 v180, v244, v170
	v_cvt_pk_bf16_f32 v181, v166, v144
	v_cvt_pk_bf16_f32 v208, v140, v132
	v_cvt_pk_bf16_f32 v209, v124, v118
	v_cvt_pk_bf16_f32 v210, v112, v108
	v_cvt_pk_bf16_f32 v211, v106, v100
	v_cvt_pk_bf16_f32 v212, v122, v134
	ds_read_b64_tr_b16 v[50:51], v0 offset:16384
	ds_read_b64_tr_b16 v[52:53], v0 offset:16896
	ds_read_b64_tr_b16 v[216:217], v0 offset:20480
	ds_read_b64_tr_b16 v[218:219], v0 offset:20992
	v_exp_f32_e32 v123, v66
	v_exp_f32_e32 v163, v82
	v_exp_f32_e32 v135, v67
	v_exp_f32_e32 v139, v83
	v_exp_f32_e32 v127, v68
	v_exp_f32_e32 v187, v70
	v_exp_f32_e32 v245, v86
	v_exp_f32_e32 v131, v84
	v_exp_f32_e32 v117, v69
	v_exp_f32_e32 v173, v85
	v_exp_f32_e32 v169, v71
	v_exp_f32_e32 v165, v72
	v_exp_f32_e32 v143, v73
	v_exp_f32_e32 v137, v74
	v_exp_f32_e32 v129, v75
	v_exp_f32_e32 v121, v76
	v_exp_f32_e32 v115, v77
	v_exp_f32_e32 v111, v78
	v_exp_f32_e32 v105, v79
	v_exp_f32_e32 v103, v80
	v_exp_f32_e32 v99, v81
	ds_read_b64_tr_b16 v[220:221], v0 offset:17408
	ds_read_b64_tr_b16 v[222:223], v0 offset:17920
	ds_read_b64_tr_b16 v[224:225], v0 offset:21504
	ds_read_b64_tr_b16 v[226:227], v0 offset:22016
	ds_read_b64_tr_b16 v[228:229], v0 offset:18432
	ds_read_b64_tr_b16 v[230:231], v0 offset:18944
	ds_read_b64_tr_b16 v[232:233], v0 offset:22528
	ds_read_b64_tr_b16 v[234:235], v0 offset:23040
	ds_read_b64_tr_b16 v[236:237], v0 offset:19456
	ds_read_b64_tr_b16 v[238:239], v0 offset:19968
	ds_read_b64_tr_b16 v[240:241], v0 offset:23552
	ds_read_b64_tr_b16 v[242:243], v0 offset:24064
	s_waitcnt lgkmcnt(14)
	v_mfma_f32_32x32x16_bf16 v[34:49], v[212:215], v[50:53], v[18:33]
	v_pk_add_f32 v[66:67], v[186:187], v[244:245]
	v_cvt_pk_bf16_f32 v68, v123, v135
	v_cvt_pk_bf16_f32 v69, v127, v117
	v_cvt_pk_bf16_f32 v70, v187, v169
	v_cvt_pk_bf16_f32 v71, v165, v143
	v_cvt_pk_bf16_f32 v72, v137, v129
	v_cvt_pk_bf16_f32 v73, v121, v115
	v_cvt_pk_bf16_f32 v74, v111, v105
	v_cvt_pk_bf16_f32 v75, v103, v99
	v_cvt_pk_bf16_f32 v76, v163, v139
	v_cvt_pk_bf16_f32 v77, v131, v173
	s_waitcnt lgkmcnt(12)
	v_mfma_f32_32x32x16_bf16 v[50:65], v[212:215], v[216:219], v[2:17]
	v_exp_f32_e32 v171, v87
	v_exp_f32_e32 v167, v88
	v_exp_f32_e32 v145, v89
	v_exp_f32_e32 v141, v90
	v_exp_f32_e32 v133, v91
	v_exp_f32_e32 v125, v92
	v_exp_f32_e32 v119, v93
	v_exp_f32_e32 v113, v94
	v_exp_f32_e32 v109, v95
	v_exp_f32_e32 v107, v96
	v_exp_f32_e32 v101, v97
	v_cvt_pk_bf16_f32 v78, v245, v171
	v_cvt_pk_bf16_f32 v79, v167, v145
	v_cvt_pk_bf16_f32 v80, v141, v133
	v_cvt_pk_bf16_f32 v81, v125, v119
	v_cvt_pk_bf16_f32 v82, v113, v109
	v_cvt_pk_bf16_f32 v83, v107, v101
	s_waitcnt lgkmcnt(10)
	v_mfma_f32_32x32x16_bf16 v[34:49], v[174:177], v[220:223], v[34:49]
	v_pk_add_f32 v[84:85], v[122:123], v[162:163]
	v_pk_add_f32 v[86:87], v[134:135], v[138:139]
	v_pk_add_f32 v[88:89], v[126:127], v[130:131]
	v_pk_add_f32 v[84:85], v[86:87], v[84:85]
	v_pk_add_f32 v[90:91], v[116:117], v[172:173]
	v_pk_add_f32 v[84:85], v[88:89], v[84:85]
	s_waitcnt lgkmcnt(8)
	v_mfma_f32_32x32x16_bf16 v[50:65], v[174:177], v[224:227], v[50:65]
	v_pk_add_f32 v[84:85], v[90:91], v[84:85]
	v_pk_add_f32 v[86:87], v[168:169], v[170:171]
	v_pk_add_f32 v[66:67], v[66:67], v[84:85]
	v_pk_add_f32 v[88:89], v[164:165], v[166:167]
	v_pk_add_f32 v[66:67], v[86:87], v[66:67]
	v_pk_add_f32 v[90:91], v[142:143], v[144:145]
	v_pk_add_f32 v[66:67], v[88:89], v[66:67]
	s_waitcnt lgkmcnt(6)
	v_mfma_f32_32x32x16_bf16 v[34:49], v[178:181], v[228:231], v[34:49]
	v_pk_add_f32 v[92:93], v[136:137], v[140:141]
	v_pk_add_f32 v[66:67], v[90:91], v[66:67]
	v_pk_add_f32 v[94:95], v[128:129], v[132:133]
	v_pk_add_f32 v[66:67], v[92:93], v[66:67]
	v_pk_add_f32 v[96:97], v[120:121], v[124:125]
	v_pk_add_f32 v[66:67], v[94:95], v[66:67]
	v_pk_add_f32 v[114:115], v[114:115], v[118:119]
	s_waitcnt lgkmcnt(4)
	v_mfma_f32_32x32x16_bf16 v[50:65], v[178:181], v[232:235], v[50:65]
	v_pk_add_f32 v[66:67], v[96:97], v[66:67]
	v_pk_add_f32 v[110:111], v[110:111], v[112:113]
	v_pk_add_f32 v[66:67], v[114:115], v[66:67]
	v_pk_add_f32 v[104:105], v[104:105], v[108:109]
	v_pk_add_f32 v[66:67], v[110:111], v[66:67]
	v_pk_add_f32 v[102:103], v[102:103], v[106:107]
	v_pk_add_f32 v[66:67], v[104:105], v[66:67]
	s_waitcnt lgkmcnt(2)
	v_mfma_f32_32x32x16_bf16 v[34:49], v[208:211], v[236:239], v[34:49]
	v_pk_add_f32 v[98:99], v[98:99], v[100:101]
	v_pk_add_f32 v[66:67], v[102:103], v[66:67]
	v_pk_add_f32 v[66:67], v[98:99], v[66:67]
	v_add_f32_e32 v66, v205, v66
	s_waitcnt lgkmcnt(0)
	v_mfma_f32_32x32x16_bf16 v[50:65], v[208:211], v[240:243], v[50:65]
	v_add_f32_e32 v66, v66, v67
	ds_read_b64_tr_b16 v[84:85], v0 offset:24576
	ds_read_b64_tr_b16 v[86:87], v0 offset:25088
	ds_read_b64_tr_b16 v[88:89], v0 offset:25600
	ds_read_b64_tr_b16 v[90:91], v0 offset:26112
	s_waitcnt lgkmcnt(2)
	v_mfma_f32_32x32x16_bf16 v[34:49], v[68:71], v[84:87], v[34:49]
	ds_read_b64_tr_b16 v[84:85], v0 offset:28672
	ds_read_b64_tr_b16 v[86:87], v0 offset:29184
	ds_read_b64_tr_b16 v[92:93], v0 offset:29696
	ds_read_b64_tr_b16 v[94:95], v0 offset:30208
	s_waitcnt lgkmcnt(2)
	v_mfma_f32_32x32x16_bf16 v[50:65], v[68:71], v[84:87], v[50:65]
	ds_read_b64_tr_b16 v[68:69], v0 offset:26624
	ds_read_b64_tr_b16 v[70:71], v0 offset:27136
	ds_read_b64_tr_b16 v[84:85], v0 offset:31744
	ds_read_b64_tr_b16 v[86:87], v0 offset:32256
	v_mfma_f32_32x32x16_bf16 v[34:49], v[72:75], v[88:91], v[34:49]
	s_waitcnt lgkmcnt(4)
	v_mfma_f32_32x32x16_bf16 v[50:65], v[72:75], v[92:95], v[50:65]
	ds_read_b64_tr_b16 v[72:73], v0 offset:27648
	ds_read_b64_tr_b16 v[74:75], v0 offset:28160
	s_waitcnt lgkmcnt(4)
	v_mfma_f32_32x32x16_bf16 v[34:49], v[76:79], v[68:71], v[34:49]
	ds_read_b64_tr_b16 v[68:69], v0 offset:30720
	ds_read_b64_tr_b16 v[70:71], v0 offset:31232
	s_waitcnt lgkmcnt(0)
	v_mfma_f32_32x32x16_bf16 v[50:65], v[76:79], v[68:71], v[50:65]
	v_mfma_f32_32x32x16_bf16 v[34:49], v[80:83], v[72:75], v[34:49]
	v_mfma_f32_32x32x16_bf16 v[50:65], v[80:83], v[84:87], v[50:65]
